# near-tile bias table reads: one base add + immediate offsets (22 fewer VALU per near step)
# baseline (speedup 1.0000x reference)
.LBB0_286:
	s_andn2_b64 vcc, exec, s[14:15]
	s_cbranch_vccnz .LBB0_288
	v_lshl_add_u32 v0, s80, 2, v207
	s_nop 8
	v_add_u32_e32 v0, 0x500, v0
	ds_read2_b32 v[114:115], v0 offset0:0 offset1:1
	ds_read2_b32 v[98:99], v0 offset0:32 offset1:33
	ds_read2_b32 v[116:117], v0 offset0:2 offset1:3
	ds_read2_b32 v[100:101], v0 offset0:34 offset1:35
	ds_read2_b32 v[118:119], v0 offset0:4 offset1:5
	ds_read2_b32 v[102:103], v0 offset0:36 offset1:37
	ds_read2_b32 v[120:121], v0 offset0:6 offset1:7
	ds_read2_b32 v[104:105], v0 offset0:38 offset1:39
	ds_read2_b32 v[122:123], v0 offset0:16 offset1:17
	ds_read2_b32 v[124:125], v0 offset0:18 offset1:19
	ds_read2_b32 v[126:127], v0 offset0:20 offset1:21
	ds_read2_b32 v[128:129], v0 offset0:22 offset1:23
	ds_read2_b32 v[106:107], v0 offset0:48 offset1:49
	ds_read2_b32 v[108:109], v0 offset0:50 offset1:51
	ds_read2_b32 v[110:111], v0 offset0:52 offset1:53
	ds_read2_b32 v[112:113], v0 offset0:54 offset1:55
	s_waitcnt lgkmcnt(4)
	v_mfma_f32_32x32x16_bf16 v[114:129], v[174:177], v[130:133], v[114:129]
	s_waitcnt lgkmcnt(0)
	v_mfma_f32_32x32x16_bf16 v[98:113], v[170:173], v[130:133], v[98:113]

.LBB0_293:
	s_andn2_b64 vcc, exec, s[0:1]
	s_cbranch_vccnz .LBB0_280
	s_nop 9
	v_lshl_add_u32 v94, s15, 2, v207
	v_add_u32_e32 v94, 0x500, v94
	ds_read2_b32 v[66:67], v94 offset0:0 offset1:1
	ds_read2_b32 v[82:83], v94 offset0:32 offset1:33
	ds_read2_b32 v[68:69], v94 offset0:2 offset1:3
	ds_read2_b32 v[84:85], v94 offset0:34 offset1:35
	ds_read2_b32 v[70:71], v94 offset0:4 offset1:5
	ds_read2_b32 v[86:87], v94 offset0:36 offset1:37
	ds_read2_b32 v[72:73], v94 offset0:6 offset1:7
	ds_read2_b32 v[88:89], v94 offset0:38 offset1:39
	ds_read2_b32 v[74:75], v94 offset0:16 offset1:17
	ds_read2_b32 v[76:77], v94 offset0:18 offset1:19
	ds_read2_b32 v[78:79], v94 offset0:20 offset1:21
	ds_read2_b32 v[80:81], v94 offset0:22 offset1:23
	ds_read2_b32 v[90:91], v94 offset0:48 offset1:49
	ds_read2_b32 v[92:93], v94 offset0:50 offset1:51
	ds_read2_b32 v[96:97], v94 offset0:54 offset1:55
	ds_read2_b32 v[94:95], v94 offset0:52 offset1:53
	s_waitcnt lgkmcnt(4)
	v_mfma_f32_32x32x16_bf16 v[66:81], v[174:177], v[130:133], v[66:81]
	s_waitcnt lgkmcnt(0)
	v_mfma_f32_32x32x16_bf16 v[82:97], v[170:173], v[130:133], v[82:97]
	s_branch .LBB0_280
